# v21 plus static priority for waves 0-3 (leading wave row) through the GEMM phases
# speedup vs baseline: 1.0001x; 1.0001x over previous
.LBB0_20:
	s_or_b64 exec, exec, s[0:1]
	v_readlane_b32 s0, v254, 20
	s_add_i32 s0, s0, 1
	s_cmp_eq_u32 s0, 4
	s_waitcnt lgkmcnt(0)
	s_barrier
	s_setprio 0
	s_cselect_b32 s100, 1, 0
	v_writelane_b32 v255, s100, 63
	v_readfirstlane_b32 s100, v198
	s_nop 1
	s_lshr_b32 s100, s100, 6
	s_cmp_ge_u32 s100, 4
	s_cbranch_scc1 .Lprio_a1
	s_setprio 1

.LBB0_185:
	s_or_b64 exec, exec, s[0:1]
	s_mov_b64 s[8:9], 0
	s_mov_b64 s[0:1], 0x7500000
	s_mov_b32 s7, 2
	s_movk_i32 s6, 0x2500
	s_waitcnt lgkmcnt(0)
	s_barrier
	s_setprio 0
	s_cselect_b32 s100, 1, 0
	v_writelane_b32 v255, s100, 63
	v_readfirstlane_b32 s100, v198
	s_nop 1
	s_lshr_b32 s100, s100, 6
	s_cmp_ge_u32 s100, 4
	s_cbranch_scc1 .Lprio_a0
	s_setprio 1

.LBB0_837:
	s_or_b64 exec, exec, s[0:1]
	s_mov_b64 s[4:5], -1
	s_waitcnt lgkmcnt(0)
	s_barrier
	s_setprio 0
	s_cselect_b32 s100, 1, 0
	v_writelane_b32 v255, s100, 63
	v_readfirstlane_b32 s100, v198
	s_nop 1
	s_lshr_b32 s100, s100, 6
	s_cmp_ge_u32 s100, 4
	s_cbranch_scc1 .Lprio_a2
	s_setprio 1

.LBB0_934:
	s_or_b64 exec, exec, s[0:1]
	s_waitcnt lgkmcnt(0)
	s_barrier
	s_setprio 0
.LBB0_935:
	s_setprio 0
	s_cselect_b32 s100, 1, 0
	v_writelane_b32 v255, s100, 63
	v_readfirstlane_b32 s100, v198
	s_nop 1
	s_lshr_b32 s100, s100, 6
	s_cmp_lt_u32 s100, 4
	s_cbranch_scc1 .Lprio_attn
	s_setprio 1

.LBB0_1244:
	s_or_b64 exec, exec, s[0:1]
	s_andn2_b64 vcc, exec, s[22:23]
	s_movk_i32 s0, 0xa00
	s_waitcnt lgkmcnt(0)
	s_barrier
	s_setprio 0
	s_cselect_b32 s100, 1, 0
	v_writelane_b32 v255, s100, 63
	v_readfirstlane_b32 s100, v198
	s_nop 1
	s_lshr_b32 s100, s100, 6
	s_cmp_ge_u32 s100, 4
	s_cbranch_scc1 .Lprio_a3
	s_setprio 1
.Lprio_a3:
	v_readlane_b32 s100, v255, 63
	s_nop 1
	s_cmp_lg_u32 s100, 0
	s_cbranch_vccnz .LBB0_1332
	s_setprio 0
	s_cselect_b32 s100, 1, 0
	v_writelane_b32 v255, s100, 63
	v_readfirstlane_b32 s100, v198
	s_nop 1
	s_lshr_b32 s100, s100, 6
	s_cmp_lt_u32 s100, 4
	s_cbranch_scc1 .Lprio_dilb
	s_setprio 1

.LBB0_1331:
	s_or_b64 exec, exec, s[0:1]
	s_movk_i32 s0, 0x500
	s_waitcnt lgkmcnt(0)
	s_barrier
	s_setprio 0
	s_cselect_b32 s100, 1, 0
	v_writelane_b32 v255, s100, 63
	v_readfirstlane_b32 s100, v198
	s_nop 1
	s_lshr_b32 s100, s100, 6
	s_cmp_ge_u32 s100, 4
	s_cbranch_scc1 .Lprio_a4
	s_setprio 1
.Lprio_a4:
	v_readlane_b32 s100, v255, 63
	s_nop 1
	s_cmp_lg_u32 s100, 0
.LBB0_1332:
	v_readlane_b32 s4, v254, 27
	v_mov_b32_e32 v20, v198
	v_readlane_b32 s5, v254, 28
	s_and_b64 vcc, exec, s[4:5]
	v_readfirstlane_b32 s18, v20
	s_cbranch_vccnz .LBB0_1368
	v_lshlrev_b32_e32 v0, 4, v20
	v_add_u32_e32 v2, 0x2000, v0
	v_ashrrev_i32_e32 v3, 31, v2
	v_lshrrev_b32_e32 v3, 22, v3
	v_add_u32_e32 v3, v2, v3
	v_ashrrev_i32_e32 v3, 10, v3
	v_mul_i32_i24_e32 v4, 0x400, v3
	v_sub_u32_e32 v2, v2, v4
	v_lshrrev_b32_e32 v4, 4, v2
	v_bitop3_b32 v2, v4, v2, 32 bitop3:0x6c
	v_ashrrev_i32_e32 v4, 31, v2
	v_lshrrev_b32_e32 v4, 26, v4
	v_add_u32_e32 v4, v2, v4
	v_lshlrev_b32_e32 v6, 3, v3
	v_ashrrev_i32_e32 v5, 6, v4
	v_and_b32_e32 v6, 0x7ffffff0, v6
	v_add_u32_e32 v5, v5, v6
	v_and_b32_e32 v4, 0xc0, v4
	v_mul_lo_u32 v14, v5, s0
	v_sub_u32_e32 v2, v2, v4
	v_mov_b32_e32 v5, 1
	v_ashrrev_i16_sdwa v2, v5, sext(v2) dst_sel:DWORD dst_unused:UNUSED_PAD src0_sel:DWORD src1_sel:BYTE_0
	v_bfe_i32 v16, v2, 0, 16
	v_bfe_i32 v2, v20, 27, 1
	v_lshlrev_b32_e32 v3, 5, v3
	v_lshrrev_b32_e32 v2, 22, v2
	v_and_b32_e32 v15, 32, v3
	v_add_u32_e32 v2, v0, v2
	v_or_b32_e32 v3, v14, v15
	v_and_b32_e32 v2, 0xfffffc00, v2
	v_add_lshl_u32 v180, v3, v16, 1
	v_sub_u32_e32 v0, v0, v2
	v_ashrrev_i32_e32 v3, 31, v20
	v_readlane_b32 s4, v254, 23
	v_lshrrev_b32_e32 v2, 4, v0
	v_lshrrev_b32_e32 v3, 26, v3
	v_readlane_b32 s5, v254, 24
	v_bitop3_b32 v2, v2, v0, 32 bitop3:0x6c
	v_ashrrev_i32_e32 v0, 31, v0
	v_add_u32_e32 v3, v20, v3
	s_and_b64 s[4:5], s[4:5], exec
	v_lshrrev_b32_e32 v0, 26, v0
	v_ashrrev_i32_e32 v3, 6, v3
	s_cselect_b32 s1, 0xa00000, 0
	v_readlane_b32 s2, v253, 4
	v_add_u32_e32 v0, v2, v0
	v_lshlrev_b32_e32 v4, 3, v3
	s_add_u32 s19, s2, s1
	v_readlane_b32 s1, v253, 5
	v_ashrrev_i32_e32 v0, 6, v0
	v_and_b32_e32 v4, 0x7ffffff0, v4
	s_addc_u32 s20, s1, 0
	s_ashr_i32 s1, s18, 6
	s_lshl_b32 s21, s0, 9
	v_add_u32_e32 v4, v0, v4
	v_mul_i32_i24_e32 v0, 64, v0
	v_readlane_b32 s8, v253, 29
	s_ashr_i32 s4, s18, 8
	s_lshl_b32 s2, s0, 8
	s_lshl_b32 s22, s1, 10
	v_lshlrev_b32_e32 v3, 5, v3
	v_sub_u32_e32 v0, v2, v0
	s_mul_hi_i32 s7, s21, s8
	s_mul_i32 s8, s21, s8
	v_mul_lo_u32 v17, v4, s0
	v_and_b32_e32 v18, 32, v3
	v_ashrrev_i16_sdwa v0, v5, sext(v0) dst_sel:DWORD dst_unused:UNUSED_PAD src0_sel:DWORD src1_sel:BYTE_0
	s_add_u32 s14, s19, s8
	v_or_b32_e32 v3, v17, v18
	v_bfe_i32 v19, v0, 0, 16
	s_addc_u32 s15, s20, s7
	s_add_i32 s23, s22, 0
	v_add_lshl_u32 v0, v3, v19, 1
	v_readlane_b32 s6, v253, 26
	v_readlane_b32 s9, v253, 30
	s_add_i32 m0, s23, 0x10000
	s_mul_hi_i32 s5, s21, s6
	s_mul_i32 s6, s21, s6
	global_load_lds_dwordx4 v0, s[14:15]
	s_add_i32 m0, s23, 0x12000
	v_readlane_b32 s8, v251, 9
	v_readlane_b32 s9, v251, 10
	s_add_u32 s12, s8, s6
	global_load_lds_dwordx4 v180, s[14:15]
	s_addc_u32 s13, s9, s5
	s_mov_b32 m0, s23
	s_add_i32 s24, s23, 0x2000
	global_load_lds_dwordx4 v0, s[12:13]
	s_mov_b32 m0, s24
	s_add_u32 s6, s14, s2
	global_load_lds_dwordx4 v180, s[12:13]
	s_addc_u32 s7, s15, 0
	s_add_i32 m0, s23, 0x14000
	v_mov_b32_e32 v181, v1
	global_load_lds_dwordx4 v0, s[6:7]
	s_add_i32 m0, s23, 0x16000
	v_lshl_add_u64 v[10:11], s[6:7], 0, v[0:1]
	v_lshl_add_u64 v[12:13], s[6:7], 0, v[180:181]
	global_load_lds_dwordx4 v180, s[6:7]
	s_add_u32 s6, s12, s2
	s_addc_u32 s7, s13, 0
	s_add_i32 s25, s23, 0x4000
	s_mov_b32 m0, s25
	s_add_i32 s26, s23, 0x6000
	global_load_lds_dwordx4 v0, s[6:7]
	s_mov_b32 m0, s26
	v_lshl_add_u64 v[2:3], s[14:15], 0, v[0:1]
	global_load_lds_dwordx4 v180, s[6:7]
	v_lshl_add_u64 v[4:5], s[14:15], 0, v[180:181]
	v_lshl_add_u64 v[6:7], s[12:13], 0, v[0:1]
	v_lshl_add_u64 v[8:9], s[12:13], 0, v[180:181]
	s_cmp_lg_u32 s4, 1
	s_cbranch_scc1 .LBB0_1335
	s_barrier
